# attention tile loop: per-wave tile limit held in an SGPR, scalar compare instead of v_cmp+s_and at the tile top
# baseline (speedup 1.0000x reference)
; template <int NS>
; __device__ __forceinline__ void attn_unit(const AUnit& u, unsigned char* lds, const bf16_t* __restrict__ GT, bf16_t* BRc, float sc, float lam, const float* __restrict__ subln) {
;     const int tid = threadIdx.x, wid = tid >> 6, lane = tid & 63, l31 = lane & 31, hh = lane >> 5;
;     const bool active = wid < u.nqw;
;     const int limit = u.causal ? u.lim0 + (wid >> 1) : u.ntiles;
;     const int qrow = u.qrow0 + wid * 32 + l31;
;     unsigned char* qs = lds + 2 * A_BUF + wid * (32 * A_KRS);
;     if (active) {
;         const bf16_t* qp = BRc + (size_t)qrow * BR + u.qcol + hh * 64;
; #pragma unroll
;         for (int i = 0; i < 8; ++i) *(u32x4*)(qs + l31 * A_KRS + hh * 128 + i * 16) = *(const u32x4*)(qp + i * 8);
;     }
;     const unsigned char* q_rd = qs + l31 * A_KRS + hh * 16;
;     f32x16 O0[4], O1[4];
;     float m0 = -1e30f, m1 = -1e30f, l0r = 0.f, l1r = 0.f;
; #pragma unroll
;     for (int d = 0; d < 4; ++d)
; #pragma unroll
;         for (int r = 0; r < 16; ++r) { O0[d][r] = 0.f; O1[d][r] = 0.f; }
;     u32x4 rk[2], rv[2];
;     attn_load1(u.kb, u.ld, 0, rk); attn_load1(u.vb, u.ld, 0, rv);
;     attn_store1(lds, A_KRS, rk); attn_store1(lds + A_KT, A_VRS, rv);
;     __syncthreads();
.LBB0_1159:
	s_or_b64 exec, exec, s[12:13]
	v_add_u32_e32 v16, s14, v208
	v_mov_b32_e32 v17, s77
	v_sub_u32_e32 v18, s15, v217
	v_mov_b32_e32 v14, v181
	v_mov_b32_e32 v15, v181
	v_mov_b32_e32 v0, v181
	v_mov_b32_e32 v1, v181
	v_mov_b32_e32 v2, v181
	v_mov_b32_e32 v3, v181
	v_mov_b32_e32 v4, v181
	v_mov_b32_e32 v5, v181
	v_mov_b32_e32 v6, v181
	v_mov_b32_e32 v7, v181
	v_mov_b32_e32 v8, v181
	v_mov_b32_e32 v9, v181
	v_mov_b32_e32 v10, v181
	v_mov_b32_e32 v11, v181
	v_mov_b32_e32 v12, v181
	v_mov_b32_e32 v13, v181
	v_cndmask_b32_e64 v193, v16, v17, s[4:5]
	v_cmp_lt_u32_e64 s[8:9], 32, v18
	v_readfirstlane_b32 s85, v193
	v_cmp_lt_u32_e64 s[10:11], 33, v18
	v_cmp_lt_u32_e64 s[12:13], 34, v18
	v_cmp_lt_u32_e64 s[14:15], 35, v18
	v_cmp_lt_u32_e64 s[16:17], 40, v18
	v_cmp_lt_u32_e64 s[18:19], 41, v18
	v_cmp_lt_u32_e64 s[20:21], 42, v18
	v_cmp_lt_u32_e64 s[22:23], 43, v18
	v_cmp_lt_u32_e64 s[24:25], 48, v18
	v_cmp_lt_u32_e64 s[26:27], 49, v18
	v_cmp_lt_u32_e64 s[28:29], 50, v18
	v_cmp_lt_u32_e64 s[30:31], 51, v18
	v_cmp_lt_u32_e64 s[34:35], 56, v18
	v_cmp_lt_u32_e64 s[36:37], 57, v18
	v_cmp_lt_u32_e64 s[38:39], 58, v18
	v_cmp_lt_u32_e64 s[40:41], 59, v18
	v_mov_b64_e32 v[46:47], v[14:15]
	v_mov_b64_e32 v[62:63], v[14:15]
	v_mov_b64_e32 v[78:79], v[14:15]
	v_mov_b64_e32 v[30:31], v[14:15]
	v_mov_b64_e32 v[94:95], v[14:15]
	v_mov_b64_e32 v[110:111], v[14:15]
	v_mov_b64_e32 v[126:127], v[14:15]
	v_add_u32_e32 v136, v212, v213
	s_add_i32 s61, s77, -1
	s_mov_b32 s42, 0
	v_mov_b32_e32 v228, 0xf149f2ca
	v_mov_b32_e32 v226, 0
	v_mov_b32_e32 v189, v177
	v_mov_b32_e32 v191, v175
	v_mov_b32_e32 v227, 0
	v_mov_b64_e32 v[44:45], v[12:13]
	v_mov_b64_e32 v[42:43], v[10:11]
	v_mov_b64_e32 v[40:41], v[8:9]
	v_mov_b64_e32 v[38:39], v[6:7]
	v_mov_b64_e32 v[36:37], v[4:5]
	v_mov_b64_e32 v[34:35], v[2:3]
	v_mov_b64_e32 v[32:33], v[0:1]
	v_mov_b64_e32 v[60:61], v[12:13]
	v_mov_b64_e32 v[58:59], v[10:11]
	v_mov_b64_e32 v[56:57], v[8:9]
	v_mov_b64_e32 v[54:55], v[6:7]
	v_mov_b64_e32 v[52:53], v[4:5]
	v_mov_b64_e32 v[50:51], v[2:3]
	v_mov_b64_e32 v[48:49], v[0:1]
	v_mov_b64_e32 v[76:77], v[12:13]
	v_mov_b64_e32 v[74:75], v[10:11]
	v_mov_b64_e32 v[72:73], v[8:9]
	v_mov_b64_e32 v[70:71], v[6:7]
	v_mov_b64_e32 v[68:69], v[4:5]
	v_mov_b64_e32 v[66:67], v[2:3]
	v_mov_b64_e32 v[64:65], v[0:1]
	v_mov_b64_e32 v[28:29], v[12:13]
	v_mov_b64_e32 v[26:27], v[10:11]
	v_mov_b64_e32 v[24:25], v[8:9]
	v_mov_b64_e32 v[22:23], v[6:7]
	v_mov_b64_e32 v[20:21], v[4:5]
	v_mov_b64_e32 v[18:19], v[2:3]
	v_mov_b64_e32 v[16:17], v[0:1]
	v_mov_b64_e32 v[92:93], v[12:13]
	v_mov_b64_e32 v[90:91], v[10:11]
	v_mov_b64_e32 v[88:89], v[8:9]
	v_mov_b64_e32 v[86:87], v[6:7]
	v_mov_b64_e32 v[84:85], v[4:5]
	v_mov_b64_e32 v[82:83], v[2:3]
	v_mov_b64_e32 v[80:81], v[0:1]
	v_mov_b64_e32 v[108:109], v[12:13]
	v_mov_b64_e32 v[106:107], v[10:11]
	v_mov_b64_e32 v[104:105], v[8:9]
	v_mov_b64_e32 v[102:103], v[6:7]
	v_mov_b64_e32 v[100:101], v[4:5]
	v_mov_b64_e32 v[98:99], v[2:3]
	v_mov_b64_e32 v[96:97], v[0:1]
	v_mov_b64_e32 v[124:125], v[12:13]
	v_mov_b64_e32 v[122:123], v[10:11]
	v_mov_b64_e32 v[120:121], v[8:9]
	v_mov_b64_e32 v[118:119], v[6:7]
	v_mov_b64_e32 v[116:117], v[4:5]
	v_mov_b64_e32 v[114:115], v[2:3]
	v_mov_b64_e32 v[112:113], v[0:1]
	v_mov_b32_e32 v229, 0xf149f2ca
	v_add_u32_e32 v137, v212, v214
	v_add_u32_e32 v138, v212, v215
	v_add_u32_e32 v139, v212, v216
	s_waitcnt vmcnt(3)
	ds_write_b128 v136, v[160:163]
	s_waitcnt vmcnt(2)
	ds_write_b128 v137, v[164:167]
	s_waitcnt vmcnt(1)
	ds_write_b128 v138, v[128:131] offset:17408
	s_waitcnt vmcnt(0)
	ds_write_b128 v139, v[132:135] offset:17408
	s_waitcnt lgkmcnt(0)
	s_barrier

; template <int NS, int SI>
; __device__ __forceinline__ void attn_stream(const unsigned char* kbase, const unsigned char* vbase, const unsigned char* q_rd, bool mask_tail, int last_valid, int hh, float sc,
;                                             f32x16 (&O)[4], float& mrun, float& lrun) {
;     ...
;     for (int k2 = 0; k2 < 8 / NS; ++k2) {
;         const int ks = SI * (8 / NS) + k2;
;         if (k2 == 2 || k2 == 4 || k2 == 6) __builtin_amdgcn_sched_barrier(0);
;         const bf16x8 qf = *(const bf16x8*)(q_rd + ks * 32);
;         const bf16x8 k0 = *(const bf16x8*)(kbase + ks * 32);
;         const bf16x8 k1 = *(const bf16x8*)(kbase + 32 * A_KRS + ks * 32);
;         S0 = __builtin_amdgcn_mfma_f32_32x32x16_bf16(k0, qf, S0, 0, 0, 0);
;         S1 = __builtin_amdgcn_mfma_f32_32x32x16_bf16(k1, qf, S1, 0, 0, 0);
;     }
;     __builtin_amdgcn_sched_barrier(0);
;     if (mask_tail) {
;         const int thr = last_valid - 4 * hh;
; #pragma unroll
;         for (int r = 0; r < 16; ++r) { if ((r & 3) + 8 * (r >> 2) >= thr) S0[r] = -1e30f; if (32 + (r & 3) + 8 * (r >> 2) >= thr) S1[r] = -1e30f; }
; template <int NS>
; __device__ __forceinline__ void attn_unit(const AUnit& u, unsigned char* lds, const bf16_t* __restrict__ GT, bf16_t* BRc, float sc, float lam, const float* __restrict__ subln) {
;     ...
;         const bool work = active && t < limit;
;         const unsigned char* kbase = lds + cur * A_BUF + k_rd;
;         const unsigned char* vbase = lds + cur * A_BUF + v_rd;
;         const bool mask_tail = (t == u.ntiles - 1) && (u.last_valid < 64);
.LBB0_1162:
	s_and_b32 s79, s42, 1
	s_cmp_lt_i32 s42, s85
	s_mul_i32 s43, s79, 0x9400
	s_cselect_b64 s[62:63], s[6:7], 0
	s_add_i32 s43, s43, 0
	s_cmp_eq_u32 s61, s42
	v_add_u32_e32 v128, s43, v210
	v_add3_u32 v225, s43, v218, v219
	s_cselect_b64 s[42:43], -1, 0
	s_and_b64 s[42:43], s[4:5], s[42:43]
	v_add_u32_e32 v230, v128, v176
	s_andn2_b64 s[42:43], exec, s[42:43]
	s_and_saveexec_b64 s[44:45], s[62:63]
	s_cbranch_execz .LBB0_1168
	ds_read_b128 v[128:131], v230
	ds_read_b128 v[144:147], v222
	ds_read_b128 v[232:235], v230 offset:32
	ds_read_b128 v[236:239], v222 offset:32
	ds_read_b128 v[148:151], v230 offset:8704
	ds_read_b128 v[240:243], v230 offset:8736
	s_waitcnt lgkmcnt(4)
	v_mfma_f32_32x32x16_bf16 v[128:143], v[128:131], v[144:147], 0
	s_waitcnt lgkmcnt(1)
	v_mfma_f32_32x32x16_bf16 v[144:159], v[148:151], v[144:147], 0
	v_mfma_f32_32x32x16_bf16 v[128:143], v[232:235], v[236:239], v[128:143]
	s_waitcnt lgkmcnt(0)
	v_mfma_f32_32x32x16_bf16 v[144:159], v[240:243], v[236:239], v[144:159]
	ds_read_b128 v[232:235], v230 offset:64
	ds_read_b128 v[236:239], v222 offset:64
	ds_read_b128 v[240:243], v230 offset:96
	ds_read_b128 v[244:247], v222 offset:96
	s_waitcnt lgkmcnt(2)
	v_mfma_f32_32x32x16_bf16 v[128:143], v[232:235], v[236:239], v[128:143]
	ds_read_b128 v[232:235], v230 offset:8768
	ds_read_b128 v[248:251], v230 offset:8800
	s_waitcnt lgkmcnt(1)
	v_mfma_f32_32x32x16_bf16 v[144:159], v[232:235], v[236:239], v[144:159]
	v_mfma_f32_32x32x16_bf16 v[128:143], v[240:243], v[244:247], v[128:143]
	s_waitcnt lgkmcnt(0)
	v_mfma_f32_32x32x16_bf16 v[144:159], v[248:251], v[244:247], v[144:159]
	s_and_b64 vcc, exec, s[42:43]
	s_cbranch_vccnz .LBB0_1165
	s_or_b64 vcc, s[40:41], s[38:39]
	s_nop 8
	v_cndmask_b32_e32 v158, v223, v158, vcc
	s_or_b64 vcc, vcc, s[36:37]
	v_cndmask_b32_e32 v157, v223, v157, vcc
	s_or_b64 vcc, vcc, s[34:35]
	v_cndmask_b32_e32 v156, v223, v156, vcc
	s_or_b64 vcc, vcc, s[30:31]
	v_cndmask_b32_e32 v155, v223, v155, vcc
	s_or_b64 vcc, vcc, s[28:29]
	v_cndmask_b32_e32 v154, v223, v154, vcc
	s_or_b64 vcc, vcc, s[26:27]
	v_cndmask_b32_e32 v153, v223, v153, vcc
	s_or_b64 vcc, vcc, s[24:25]
	v_cndmask_b32_e32 v152, v223, v152, vcc
	s_or_b64 vcc, vcc, s[22:23]
	v_cndmask_b32_e32 v151, v223, v151, vcc
	s_or_b64 vcc, vcc, s[20:21]
	v_cndmask_b32_e32 v150, v223, v150, vcc
	s_or_b64 vcc, vcc, s[18:19]
	v_cndmask_b32_e32 v149, v223, v149, vcc
	s_or_b64 vcc, vcc, s[16:17]
	v_cndmask_b32_e32 v148, v223, v148, vcc
	s_or_b64 vcc, vcc, s[14:15]
	v_cndmask_b32_e32 v147, v223, v147, vcc
	s_or_b64 vcc, vcc, s[12:13]
	v_cndmask_b32_e32 v146, v223, v146, vcc
	s_or_b64 vcc, vcc, s[10:11]
	v_cndmask_b32_e32 v145, v223, v145, vcc
	s_or_b64 vcc, vcc, s[8:9]
	v_cndmask_b32_e64 v159, v223, v159, s[40:41]
	v_cndmask_b32_e32 v144, v223, v144, vcc
